# dense attention loops: back edge rotated - next tile's read-buffer base and K fragment LDS addresses formed before the closing barrier, loop head starts with the ds_reads
# speedup vs baseline: 1.0093x; 1.0093x over previous
.Lam96_sk2_c:
	v_add_u32_e32 v138, s3, v134
	v_mad_i64_i32 v[140:141], s[42:43], v138, s82, 0
	v_mov_b32_e32 v142, s90
	v_mov_b32_e32 v143, s91
	v_lshl_add_u64 v[140:141], v[140:141], 1, v[142:143]
	v_lshl_add_u64 v[140:141], v[140:141], 0, s[0:1]
	v_lshl_add_u64 v[244:245], v[140:141], 0, v[0:1]
	v_mov_b32_e32 v136, s11
	v_mov_b32_e32 v137, 0
	v_sub_f32_e32 v216, 0, v132
	v_sub_f32_e32 v217, 0, v132
	v_sub_f32_e32 v218, 0, v132
	v_sub_f32_e32 v219, 0, v132
	v_sub_f32_e32 v220, 0, v132
	v_sub_f32_e32 v221, 0, v132
	v_sub_f32_e32 v222, 0, v132
	v_sub_f32_e32 v223, 0, v132
	v_sub_f32_e32 v224, 0, v132
	v_sub_f32_e32 v225, 0, v132
	v_sub_f32_e32 v226, 0, v132
	v_sub_f32_e32 v227, 0, v132
	v_sub_f32_e32 v228, 0, v132
	v_sub_f32_e32 v229, 0, v132
	v_sub_f32_e32 v230, 0, v132
	v_sub_f32_e32 v231, 0, v132
	s_add_i32 s10, s25, -1
	s_bitcmp1_b32 s10, 0
	s_cselect_b32 s2, 0x5000, 0
	v_add_u32_e32 v138, s2, v125
	v_add_u32_e32 v139, s2, v126
.Lam96_top:
	ds_read_b128 v[148:151], v138
	ds_read_b128 v[152:155], v139
	ds_read_b128 v[156:159], v138 offset:64
	ds_read_b128 v[160:163], v139 offset:64
	ds_read_b128 v[164:167], v138 offset:128
	ds_read_b128 v[168:171], v139 offset:128
	ds_read_b128 v[172:175], v138 offset:6144
	ds_read_b128 v[176:179], v139 offset:6144
	ds_read_b128 v[180:183], v138 offset:6208
	ds_read_b128 v[184:187], v139 offset:6208
	ds_read_b128 v[188:191], v138 offset:6272
	ds_read_b128 v[192:195], v139 offset:6272
	s_add_i32 s10, s25, -1
	s_cmp_lg_u32 s10, 7
	s_cbranch_scc1 .Lam96_ptr_ok
	s_movk_i32 s50, 0xff80
	s_mov_b32 s51, -1
	s_lshl_b32 s11, s84, 7
	v_add_u32_e32 v138, s24, v135
	v_add_u32_e32 v138, 0x180, v138
	v_ashrrev_i32_e32 v139, 31, v138
	s_and_saveexec_b64 s[26:27], vcc
	v_mad_i64_i32 v[140:141], s[42:43], v138, s84, 0
	v_mov_b32_e32 v142, s70
	v_mov_b32_e32 v143, s71
	v_lshl_add_u64 v[140:141], v[140:141], 1, v[142:143]
	v_lshl_add_u64 v[140:141], v[140:141], 0, s[0:1]
	v_lshl_add_u64 v[240:241], v[108:109], 1, v[140:141]
	v_mov_b32_e32 v246, s11
	s_andn2_b64 exec, s[26:27], vcc
	v_lshlrev_b64 v[140:141], 6, v[138:139]
	v_lshl_add_u64 v[140:141], s[20:21], 0, v[140:141]
	v_lshl_add_u64 v[140:141], v[110:111], 1, v[140:141]
	v_lshl_add_u64 v[240:241], v[140:141], 0, s[50:51]
	v_mov_b32_e32 v246, 0x1000
	s_mov_b64 exec, s[26:27]
	v_mov_b32_e32 v247, 0
	s_and_b64 s[48:49], exec, s[38:39]
	s_cbranch_scc0 .Lam96_sk2_l
	v_add_u32_e32 v138, s24, v133
	v_add_u32_e32 v138, 0x180, v138
	v_ashrrev_i32_e32 v139, 31, v138
	s_and_saveexec_b64 s[26:27], s[40:41]
	v_mad_i64_i32 v[140:141], s[42:43], v138, s84, 0
	v_mov_b32_e32 v142, s70
	v_mov_b32_e32 v143, s71
	v_lshl_add_u64 v[140:141], v[140:141], 1, v[142:143]
	v_lshl_add_u64 v[140:141], v[140:141], 0, s[0:1]
	v_lshl_add_u64 v[242:243], v[112:113], 1, v[140:141]
	v_mov_b32_e32 v208, s11
	s_andn2_b64 exec, s[26:27], s[40:41]
	v_lshlrev_b64 v[140:141], 6, v[138:139]
	v_lshl_add_u64 v[140:141], s[20:21], 0, v[140:141]
	v_lshl_add_u64 v[140:141], v[114:115], 1, v[140:141]
	v_lshl_add_u64 v[242:243], v[140:141], 0, s[50:51]
	v_mov_b32_e32 v208, 0x1000
	s_mov_b64 exec, s[26:27]
	v_mov_b32_e32 v209, 0

.Lam96_nos2:
	s_waitcnt vmcnt(0)
	ds_write_b128 v140, v[98:101] offset:12288
	s_add_i32 s25, s25, 1
	s_mov_b32 s2, s26
	v_add_u32_e32 v138, s26, v125
	v_add_u32_e32 v139, s26, v126
	s_cmp_lg_u32 s25, 40
	s_waitcnt lgkmcnt(0)
	s_barrier
	s_cbranch_scc1 .Lam96_top
	s_mov_b32 s2, 0x41000000
	s_setprio 0
	s_branch .LBB0_333

.Lad64_noprio:
	v_add_u32_e32 v134, s3, v118
	v_mad_i64_i32 v[246:247], s[26:27], v134, s82, 0
	v_mov_b32_e32 v208, s86
	v_mov_b32_e32 v209, s87
	v_lshl_add_u64 v[208:209], v[246:247], 1, v[208:209]
	v_lshl_add_u64 v[208:209], v[208:209], 0, s[0:1]
	v_lshl_add_u64 v[240:241], v[92:93], 1, v[208:209]
	v_add_u32_e32 v134, s3, v117
	v_mad_i64_i32 v[246:247], s[26:27], v134, s82, 0
	v_mov_b32_e32 v208, s90
	v_mov_b32_e32 v209, s91
	v_lshl_add_u64 v[208:209], v[246:247], 1, v[208:209]
	v_lshl_add_u64 v[208:209], v[208:209], 0, s[0:1]
	v_lshl_add_u64 v[242:243], v[208:209], 0, v[0:1]
	s_lshl_b32 s26, s82, 7
	v_mov_b32_e32 v244, s26
	v_mov_b32_e32 v245, 0
	v_mov_b32_e32 v239, v118
	s_mov_b32 s2, 0x41000000
	v_sub_f32_e32 v118, 0, v112
	v_sub_f32_e32 v119, 0, v112
	v_sub_f32_e32 v120, 0, v112
	v_sub_f32_e32 v121, 0, v112
	v_sub_f32_e32 v122, 0, v112
	v_sub_f32_e32 v123, 0, v112
	v_sub_f32_e32 v124, 0, v112
	v_sub_f32_e32 v125, 0, v112
	v_sub_f32_e32 v126, 0, v112
	v_sub_f32_e32 v127, 0, v112
	v_sub_f32_e32 v128, 0, v112
	v_sub_f32_e32 v129, 0, v112
	v_sub_f32_e32 v130, 0, v112
	v_sub_f32_e32 v131, 0, v112
	v_sub_f32_e32 v132, 0, v112
	v_sub_f32_e32 v133, 0, v112
	s_add_i32 s25, s24, 0xffffc000
	s_and_b32 s25, s25, 0x4000
	v_add_u32_e32 v134, s25, v98
	v_add_u32_e32 v117, s25, v109
	v_add_u32_e32 v208, s25, v111
	v_add_u32_e32 v209, s25, v114
.Lad64_top:
	ds_read_b128 v[148:151], v134
	ds_read_b128 v[152:155], v117
	ds_read_b128 v[156:159], v208
	ds_read_b128 v[160:163], v209
	ds_read_b128 v[164:167], v134 offset:4096
	ds_read_b128 v[168:171], v117 offset:4096
	ds_read_b128 v[172:175], v208 offset:4096
	ds_read_b128 v[176:179], v209 offset:4096
	s_cmp_lg_u32 s10, 7
	s_cbranch_scc1 .Lad64_ptr_ok
	v_add_u32_e32 v134, s11, v239
	v_add_u32_e32 v134, 0x180, v134
	v_mad_i64_i32 v[246:247], s[26:27], v134, s84, 0
	v_mov_b32_e32 v208, s70
	v_mov_b32_e32 v209, s71
	v_lshl_add_u64 v[208:209], v[246:247], 1, v[208:209]
	v_lshl_add_u64 v[208:209], v[208:209], 0, s[0:1]
	v_lshl_add_u64 v[240:241], v[92:93], 1, v[208:209]
	v_mov_b32_e32 v208, s6
	v_mov_b32_e32 v209, s7
	v_lshl_add_u64 v[208:209], v[246:247], 1, v[208:209]
	v_lshl_add_u64 v[208:209], v[208:209], 0, s[0:1]
	v_lshl_add_u64 v[242:243], v[208:209], 0, v[0:1]
	s_lshl_b32 s26, s84, 7
	v_mov_b32_e32 v244, s26

.Lad64_exp:
	v_exp_f32_e32 v34, v34
	v_exp_f32_e32 v35, v35
	v_exp_f32_e32 v36, v36
	v_exp_f32_e32 v37, v37
	v_exp_f32_e32 v38, v38
	v_exp_f32_e32 v39, v39
	v_exp_f32_e32 v40, v40
	v_exp_f32_e32 v41, v41
	v_cvt_pk_bf16_f32 v220, v34, v35
	v_cvt_pk_bf16_f32 v221, v36, v37
	v_cvt_pk_bf16_f32 v222, v38, v39
	v_cvt_pk_bf16_f32 v223, v40, v41
	v_add_f32_e32 v208, v34, v35
	v_add_f32_e32 v209, v36, v37
	v_add_f32_e32 v208, v208, v38
	v_add_f32_e32 v209, v209, v39
	v_add_f32_e32 v208, v208, v40
	v_add_f32_e32 v209, v209, v41
	v_add_f32_e32 v96, v96, v208
	v_add_f32_e32 v96, v96, v209
	s_waitcnt lgkmcnt(10)
	v_mfma_f32_32x32x16_bf16 v[18:33], v[180:183], v[220:223], v[18:33]
	s_waitcnt lgkmcnt(8)
	v_mfma_f32_32x32x16_bf16 v[2:17], v[184:187], v[220:223], v[2:17]
	ds_read_b64_tr_b16 v[204:205], v134 offset:14336
	ds_read_b64_tr_b16 v[206:207], v134 offset:15360
	ds_read_b64_tr_b16 v[216:217], v117 offset:14336
	ds_read_b64_tr_b16 v[218:219], v117 offset:15360
	v_exp_f32_e32 v42, v42
	v_exp_f32_e32 v43, v43
	v_exp_f32_e32 v44, v44
	v_exp_f32_e32 v45, v45
	v_exp_f32_e32 v46, v46
	v_exp_f32_e32 v47, v47
	v_exp_f32_e32 v48, v48
	v_exp_f32_e32 v49, v49
	v_cvt_pk_bf16_f32 v224, v42, v43
	v_cvt_pk_bf16_f32 v225, v44, v45
	v_cvt_pk_bf16_f32 v226, v46, v47
	v_cvt_pk_bf16_f32 v227, v48, v49
	v_add_f32_e32 v208, v42, v43
	v_add_f32_e32 v209, v44, v45
	v_add_f32_e32 v208, v208, v46
	v_add_f32_e32 v209, v209, v47
	v_add_f32_e32 v208, v208, v48
	v_add_f32_e32 v209, v209, v49
	v_add_f32_e32 v96, v96, v208
	v_add_f32_e32 v96, v96, v209
	s_waitcnt lgkmcnt(10)
	v_mfma_f32_32x32x16_bf16 v[18:33], v[188:191], v[224:227], v[18:33]
	s_waitcnt lgkmcnt(8)
	v_mfma_f32_32x32x16_bf16 v[2:17], v[192:195], v[224:227], v[2:17]
	v_exp_f32_e32 v50, v50
	v_exp_f32_e32 v51, v51
	v_exp_f32_e32 v52, v52
	v_exp_f32_e32 v53, v53
	v_exp_f32_e32 v54, v54
	v_exp_f32_e32 v55, v55
	v_exp_f32_e32 v56, v56
	v_exp_f32_e32 v57, v57
	v_cvt_pk_bf16_f32 v228, v50, v51
	v_cvt_pk_bf16_f32 v229, v52, v53
	v_cvt_pk_bf16_f32 v230, v54, v55
	v_cvt_pk_bf16_f32 v231, v56, v57
	v_add_f32_e32 v208, v50, v51
	v_add_f32_e32 v209, v52, v53
	v_add_f32_e32 v208, v208, v54
	v_add_f32_e32 v209, v209, v55
	v_add_f32_e32 v208, v208, v56
	v_add_f32_e32 v209, v209, v57
	v_add_f32_e32 v96, v96, v208
	v_add_f32_e32 v96, v96, v209
	s_waitcnt lgkmcnt(6)
	v_mfma_f32_32x32x16_bf16 v[18:33], v[196:199], v[228:231], v[18:33]
	s_waitcnt lgkmcnt(4)
	v_mfma_f32_32x32x16_bf16 v[2:17], v[200:203], v[228:231], v[2:17]
	v_exp_f32_e32 v58, v58
	v_exp_f32_e32 v59, v59
	v_exp_f32_e32 v60, v60
	v_exp_f32_e32 v61, v61
	v_exp_f32_e32 v62, v62
	v_exp_f32_e32 v63, v63
	v_exp_f32_e32 v64, v64
	v_exp_f32_e32 v65, v65
	v_cvt_pk_bf16_f32 v232, v58, v59
	v_cvt_pk_bf16_f32 v233, v60, v61
	v_cvt_pk_bf16_f32 v234, v62, v63
	v_cvt_pk_bf16_f32 v235, v64, v65
	v_add_f32_e32 v208, v58, v59
	v_add_f32_e32 v209, v60, v61
	v_add_f32_e32 v208, v208, v62
	v_add_f32_e32 v209, v209, v63
	v_add_f32_e32 v208, v208, v64
	v_add_f32_e32 v209, v209, v65
	v_add_f32_e32 v96, v96, v208
	v_add_f32_e32 v96, v96, v209
	s_waitcnt lgkmcnt(2)
	v_mfma_f32_32x32x16_bf16 v[18:33], v[204:207], v[232:235], v[18:33]
	s_waitcnt lgkmcnt(0)
	v_mfma_f32_32x32x16_bf16 v[2:17], v[216:219], v[232:235], v[2:17]
	s_and_b32 s26, s24, 0x4000
	v_add3_u32 v134, s26, v106, v101
	v_add3_u32 v117, s26, v97, v99
	s_waitcnt vmcnt(1)
	ds_write_b128 v134, v[82:85]
	s_waitcnt vmcnt(0)
	ds_write_b128 v117, v[86:89] offset:8192
	s_add_i32 s10, s10, 1
	s_addk_i32 s24, 0x4000
	s_mov_b32 s25, s26
	v_add_u32_e32 v134, s26, v98
	v_add_u32_e32 v117, s26, v109
	v_add_u32_e32 v208, s26, v111
	v_add_u32_e32 v209, s26, v114
	s_cmp_lg_u32 s10, 39
	s_waitcnt lgkmcnt(0)
	s_barrier
	s_cbranch_scc1 .Lad64_top
	s_setprio 0
	s_branch .LBB0_345
